# prep-wave bonus*v store packs bf16 with v_cvt_pk_bf16_f32 instead of the bit trick
# baseline (speedup 1.0000x reference)
.LBB0_971:
	s_cmp_eq_u32 s16, 0x7f0000
	s_cbranch_scc1 .LBB0_951
	v_lshlrev_b32_e32 v94, 16, v113
	v_and_b32_e32 v95, 0xffff0000, v113
	v_lshlrev_b32_e32 v96, 16, v116
	v_and_b32_e32 v97, 0xffff0000, v116
	v_pk_add_f32 v[96:97], v[96:97], v[94:95] neg_lo:[0,1] neg_hi:[0,1]
	v_lshlrev_b32_e32 v90, 16, v112
	v_and_b32_e32 v91, 0xffff0000, v112
	v_lshlrev_b32_e32 v92, 16, v115
	v_and_b32_e32 v93, 0xffff0000, v115
	v_pk_fma_f32 v[96:97], v[38:39], v[96:97], v[94:95]
	v_pk_add_f32 v[92:93], v[92:93], v[90:91] neg_lo:[0,1] neg_hi:[0,1]
	v_pk_mul_f32 v[94:95], v[36:37], v[96:97]
	v_pk_fma_f32 v[90:91], v[32:33], v[92:93], v[90:91]
	v_lshlrev_b32_e32 v92, 16, v120
	v_and_b32_e32 v93, 0xffff0000, v120
	v_pk_mul_f32 v[144:145], v[94:95], v[94:95]
	v_lshlrev_b32_e32 v98, 16, v114
	v_add_f32_e32 v44, v144, v145
	v_pk_add_f32 v[144:145], v[92:93], -1.0 op_sel_hi:[1,0]
	v_and_b32_e32 v99, 0xffff0000, v114
	v_pk_fma_f32 v[144:145], v[40:41], v[144:145], 1.0 op_sel_hi:[1,1,0]
	v_add_f32_dpp v44, v44, v44 quad_perm:[1,0,3,2] row_mask:0xf bank_mask:0xf bound_ctrl:1
	v_pk_mul_f32 v[96:97], v[96:97], v[144:145]
	v_lshlrev_b32_e32 v146, 16, v119
	v_pk_mul_f32 v[144:145], v[90:91], v[96:97]
	v_add_f32_dpp v44, v44, v44 quad_perm:[2,3,0,1] row_mask:0xf bank_mask:0xf bound_ctrl:1
	v_mul_f32_e32 v143, v43, v145
	v_fmac_f32_e32 v143, v42, v144
	v_add_f32_dpp v44, v44, v44 row_half_mirror row_mask:0xf bank_mask:0xf bound_ctrl:1
	v_and_b32_e32 v147, 0xffff0000, v119
	v_add_f32_dpp v143, v143, v143 quad_perm:[1,0,3,2] row_mask:0xf bank_mask:0xf bound_ctrl:1
	v_add_f32_dpp v44, v44, v44 row_mirror row_mask:0xf bank_mask:0xf bound_ctrl:1
	ds_bpermute_b32 v87, v102, v44
	v_add_f32_dpp v143, v143, v143 quad_perm:[2,3,0,1] row_mask:0xf bank_mask:0xf bound_ctrl:1
	v_pk_add_f32 v[146:147], v[146:147], v[98:99] neg_lo:[0,1] neg_hi:[0,1]
	s_nop 0
	v_add_f32_dpp v143, v143, v143 row_half_mirror row_mask:0xf bank_mask:0xf bound_ctrl:1
	v_pk_fma_f32 v[98:99], v[34:35], v[146:147], v[98:99]
	s_nop 0
	v_add_f32_dpp v143, v143, v143 row_mirror row_mask:0xf bank_mask:0xf bound_ctrl:1
	ds_bpermute_b32 v144, v102, v143
	s_and_saveexec_b64 s[4:5], s[0:1]
	s_cbranch_execz .LBB0_974
	s_waitcnt lgkmcnt(0)
	v_add_f32_e32 v144, v143, v144
	v_pk_mul_f32 v[144:145], v[98:99], v[144:145] op_sel_hi:[1,0]
	v_cvt_pk_bf16_f32 v143, v144, v145
	v_lshl_add_u64 v[144:145], v[78:79], 0, s[16:17]
	global_store_dword v[144:145], v143, off
.LBB0_974:
	s_or_b64 exec, exec, s[4:5]
	s_waitcnt lgkmcnt(1)
	v_add_f32_e32 v44, v44, v87
	s_bitcmp1_b32 s29, 0
	v_and_b32_e32 v147, 0xffff0000, v124
	s_waitcnt lgkmcnt(0)
	s_cselect_b32 s4, 0xc000, 0
	s_add_i32 s22, s4, 0
	v_max_f32_e32 v87, 0x179abe15, v44
	v_rsq_f32_e32 v144, v87
	s_nop 0
	v_lshlrev_b32_e32 v44, 2, v101
	v_pk_mul_f32 v[94:95], v[94:95], v[144:145] op_sel_hi:[1,0] neg_lo:[0,1] neg_hi:[0,1]
	v_add3_u32 v87, s22, v104, v44
	v_pk_mul_f32 v[92:93], v[94:95], v[92:93] neg_lo:[1,0] neg_hi:[1,0]
	ds_write2_b64 v87, v[48:49], v[96:97] offset1:32
	ds_write2_b64 v87, v[94:95], v[92:93] offset0:64 offset1:96
	ds_write2_b64 v87, v[90:91], v[98:99] offset0:128 offset1:160
	v_lshlrev_b32_e32 v94, 16, v121
	v_and_b32_e32 v95, 0xffff0000, v121
	v_lshlrev_b32_e32 v96, 16, v123
	v_and_b32_e32 v97, 0xffff0000, v123
	v_pk_add_f32 v[96:97], v[96:97], v[94:95] neg_lo:[0,1] neg_hi:[0,1]
	v_lshlrev_b32_e32 v90, 16, v128
	v_and_b32_e32 v91, 0xffff0000, v128
	v_lshlrev_b32_e32 v92, 16, v122
	v_and_b32_e32 v93, 0xffff0000, v122
	v_pk_fma_f32 v[96:97], v[38:39], v[96:97], v[94:95]
	v_pk_add_f32 v[92:93], v[92:93], v[90:91] neg_lo:[0,1] neg_hi:[0,1]
	v_pk_mul_f32 v[94:95], v[36:37], v[96:97]
	v_pk_fma_f32 v[90:91], v[32:33], v[92:93], v[90:91]
	v_lshlrev_b32_e32 v92, 16, v125
	v_and_b32_e32 v93, 0xffff0000, v125
	v_pk_mul_f32 v[144:145], v[94:95], v[94:95]
	v_lshlrev_b32_e32 v98, 16, v129
	v_add_f32_e32 v87, v144, v145
	v_pk_add_f32 v[144:145], v[92:93], -1.0 op_sel_hi:[1,0]
	v_and_b32_e32 v99, 0xffff0000, v129
	v_pk_fma_f32 v[144:145], v[40:41], v[144:145], 1.0 op_sel_hi:[1,1,0]
	v_add_f32_dpp v87, v87, v87 quad_perm:[1,0,3,2] row_mask:0xf bank_mask:0xf bound_ctrl:1
	v_pk_mul_f32 v[96:97], v[96:97], v[144:145]
	v_lshlrev_b32_e32 v146, 16, v124
	v_pk_mul_f32 v[144:145], v[90:91], v[96:97]
	v_add_f32_dpp v87, v87, v87 quad_perm:[2,3,0,1] row_mask:0xf bank_mask:0xf bound_ctrl:1
	v_mul_f32_e32 v145, v43, v145
	v_fmac_f32_e32 v145, v42, v144
	v_add_f32_dpp v87, v87, v87 row_half_mirror row_mask:0xf bank_mask:0xf bound_ctrl:1
	v_pk_add_f32 v[146:147], v[146:147], v[98:99] neg_lo:[0,1] neg_hi:[0,1]
	v_add_f32_dpp v144, v145, v145 quad_perm:[1,0,3,2] row_mask:0xf bank_mask:0xf bound_ctrl:1
	v_add_f32_dpp v87, v87, v87 row_mirror row_mask:0xf bank_mask:0xf bound_ctrl:1
	ds_bpermute_b32 v143, v102, v87
	v_add_f32_dpp v144, v144, v144 quad_perm:[2,3,0,1] row_mask:0xf bank_mask:0xf bound_ctrl:1
	v_pk_fma_f32 v[98:99], v[34:35], v[146:147], v[98:99]
	s_nop 0
	v_add_f32_dpp v144, v144, v144 row_half_mirror row_mask:0xf bank_mask:0xf bound_ctrl:1
	s_nop 1
	v_add_f32_dpp v144, v144, v144 row_mirror row_mask:0xf bank_mask:0xf bound_ctrl:1
	ds_bpermute_b32 v145, v102, v144
	s_and_saveexec_b64 s[4:5], s[0:1]
	s_cbranch_execz .LBB0_976
	s_waitcnt lgkmcnt(0)
	v_add_f32_e32 v144, v144, v145
	v_pk_mul_f32 v[144:145], v[98:99], v[144:145] op_sel_hi:[1,0]
	v_cvt_pk_bf16_f32 v146, v144, v145
	v_lshl_add_u64 v[144:145], v[84:85], 0, s[16:17]
	global_store_dword v[144:145], v146, off
.LBB0_976:
	s_or_b64 exec, exec, s[4:5]
	s_waitcnt lgkmcnt(1)
	v_add_f32_e32 v87, v87, v143
	s_waitcnt lgkmcnt(0)
	v_max_f32_e32 v143, 0x179abe15, v87
	v_rsq_f32_e32 v144, v143
	s_nop 0
	v_pk_mul_f32 v[94:95], v[94:95], v[144:145] op_sel_hi:[1,0] neg_lo:[0,1] neg_hi:[0,1]
	v_add3_u32 v87, s22, v108, v44
	v_pk_mul_f32 v[92:93], v[94:95], v[92:93] neg_lo:[1,0] neg_hi:[1,0]
	ds_write2_b64 v87, v[50:51], v[96:97] offset1:32
	ds_write2_b64 v87, v[94:95], v[92:93] offset0:64 offset1:96
	ds_write2_b64 v87, v[90:91], v[98:99] offset0:128 offset1:160
	v_lshlrev_b32_e32 v94, 16, v126
	v_and_b32_e32 v95, 0xffff0000, v126
	v_lshlrev_b32_e32 v96, 16, v130
	v_and_b32_e32 v97, 0xffff0000, v130
	v_pk_add_f32 v[96:97], v[96:97], v[94:95] neg_lo:[0,1] neg_hi:[0,1]
	v_lshlrev_b32_e32 v90, 16, v133
	v_and_b32_e32 v91, 0xffff0000, v133
	v_lshlrev_b32_e32 v92, 16, v127
	v_and_b32_e32 v93, 0xffff0000, v127
	v_pk_fma_f32 v[96:97], v[38:39], v[96:97], v[94:95]
	v_pk_add_f32 v[92:93], v[92:93], v[90:91] neg_lo:[0,1] neg_hi:[0,1]
	v_pk_mul_f32 v[94:95], v[36:37], v[96:97]
	v_pk_fma_f32 v[90:91], v[32:33], v[92:93], v[90:91]
	v_lshlrev_b32_e32 v92, 16, v132
	v_and_b32_e32 v93, 0xffff0000, v132
	v_pk_mul_f32 v[144:145], v[94:95], v[94:95]
	v_lshlrev_b32_e32 v98, 16, v134
	v_add_f32_e32 v87, v144, v145
	v_pk_add_f32 v[144:145], v[92:93], -1.0 op_sel_hi:[1,0]
	v_and_b32_e32 v99, 0xffff0000, v134
	v_pk_fma_f32 v[144:145], v[40:41], v[144:145], 1.0 op_sel_hi:[1,1,0]
	v_add_f32_dpp v87, v87, v87 quad_perm:[1,0,3,2] row_mask:0xf bank_mask:0xf bound_ctrl:1
	v_pk_mul_f32 v[96:97], v[96:97], v[144:145]
	v_lshlrev_b32_e32 v146, 16, v131
	v_pk_mul_f32 v[144:145], v[90:91], v[96:97]
	v_add_f32_dpp v87, v87, v87 quad_perm:[2,3,0,1] row_mask:0xf bank_mask:0xf bound_ctrl:1
	v_mul_f32_e32 v145, v43, v145
	v_fmac_f32_e32 v145, v42, v144
	v_add_f32_dpp v87, v87, v87 row_half_mirror row_mask:0xf bank_mask:0xf bound_ctrl:1
	v_and_b32_e32 v147, 0xffff0000, v131
	v_add_f32_dpp v144, v145, v145 quad_perm:[1,0,3,2] row_mask:0xf bank_mask:0xf bound_ctrl:1
	v_add_f32_dpp v87, v87, v87 row_mirror row_mask:0xf bank_mask:0xf bound_ctrl:1
	ds_bpermute_b32 v143, v102, v87
	v_add_f32_dpp v144, v144, v144 quad_perm:[2,3,0,1] row_mask:0xf bank_mask:0xf bound_ctrl:1
	v_pk_add_f32 v[146:147], v[146:147], v[98:99] neg_lo:[0,1] neg_hi:[0,1]
	s_nop 0
	v_add_f32_dpp v144, v144, v144 row_half_mirror row_mask:0xf bank_mask:0xf bound_ctrl:1
	v_pk_fma_f32 v[98:99], v[34:35], v[146:147], v[98:99]
	s_nop 0
	v_add_f32_dpp v144, v144, v144 row_mirror row_mask:0xf bank_mask:0xf bound_ctrl:1
	ds_bpermute_b32 v145, v102, v144
	s_and_saveexec_b64 s[4:5], s[0:1]
	s_cbranch_execz .LBB0_978
	s_waitcnt lgkmcnt(0)
	v_add_f32_e32 v144, v144, v145
	v_pk_mul_f32 v[144:145], v[98:99], v[144:145] op_sel_hi:[1,0]
	v_cvt_pk_bf16_f32 v146, v144, v145
	v_lshl_add_u64 v[144:145], v[82:83], 0, s[16:17]
	global_store_dword v[144:145], v146, off
.LBB0_978:
	s_or_b64 exec, exec, s[4:5]
	s_waitcnt lgkmcnt(1)
	v_add_f32_e32 v87, v87, v143
	s_waitcnt lgkmcnt(0)
	v_max_f32_e32 v143, 0x179abe15, v87
	v_rsq_f32_e32 v144, v143
	s_nop 0
	v_pk_mul_f32 v[94:95], v[94:95], v[144:145] op_sel_hi:[1,0] neg_lo:[0,1] neg_hi:[0,1]
	v_add3_u32 v87, s22, v109, v44
	v_pk_mul_f32 v[92:93], v[94:95], v[92:93] neg_lo:[1,0] neg_hi:[1,0]
	ds_write2_b64 v87, v[74:75], v[96:97] offset1:32
	ds_write2_b64 v87, v[94:95], v[92:93] offset0:64 offset1:96
	ds_write2_b64 v87, v[90:91], v[98:99] offset0:128 offset1:160
	v_lshlrev_b32_e32 v94, 16, v136
	v_and_b32_e32 v95, 0xffff0000, v136
	v_lshlrev_b32_e32 v96, 16, v138
	v_and_b32_e32 v97, 0xffff0000, v138
	v_pk_add_f32 v[96:97], v[96:97], v[94:95] neg_lo:[0,1] neg_hi:[0,1]
	v_lshlrev_b32_e32 v90, 16, v140
	v_and_b32_e32 v91, 0xffff0000, v140
	v_lshlrev_b32_e32 v92, 16, v137
	v_and_b32_e32 v93, 0xffff0000, v137
	v_pk_fma_f32 v[96:97], v[38:39], v[96:97], v[94:95]
	v_pk_add_f32 v[92:93], v[92:93], v[90:91] neg_lo:[0,1] neg_hi:[0,1]
	v_pk_mul_f32 v[94:95], v[36:37], v[96:97]
	v_pk_fma_f32 v[90:91], v[32:33], v[92:93], v[90:91]
	v_lshlrev_b32_e32 v92, 16, v142
	v_and_b32_e32 v93, 0xffff0000, v142
	v_pk_mul_f32 v[144:145], v[94:95], v[94:95]
	v_lshlrev_b32_e32 v98, 16, v141
	v_add_f32_e32 v87, v144, v145
	v_pk_add_f32 v[144:145], v[92:93], -1.0 op_sel_hi:[1,0]
	v_and_b32_e32 v99, 0xffff0000, v141
	v_pk_fma_f32 v[144:145], v[40:41], v[144:145], 1.0 op_sel_hi:[1,1,0]
	v_add_f32_dpp v87, v87, v87 quad_perm:[1,0,3,2] row_mask:0xf bank_mask:0xf bound_ctrl:1
	v_pk_mul_f32 v[96:97], v[96:97], v[144:145]
	v_lshlrev_b32_e32 v146, 16, v139
	v_pk_mul_f32 v[144:145], v[90:91], v[96:97]
	v_add_f32_dpp v87, v87, v87 quad_perm:[2,3,0,1] row_mask:0xf bank_mask:0xf bound_ctrl:1
	v_mul_f32_e32 v145, v43, v145
	v_fmac_f32_e32 v145, v42, v144
	v_add_f32_dpp v87, v87, v87 row_half_mirror row_mask:0xf bank_mask:0xf bound_ctrl:1
	v_and_b32_e32 v147, 0xffff0000, v139
	v_add_f32_dpp v144, v145, v145 quad_perm:[1,0,3,2] row_mask:0xf bank_mask:0xf bound_ctrl:1
	v_add_f32_dpp v87, v87, v87 row_mirror row_mask:0xf bank_mask:0xf bound_ctrl:1
	ds_bpermute_b32 v143, v102, v87
	v_add_f32_dpp v144, v144, v144 quad_perm:[2,3,0,1] row_mask:0xf bank_mask:0xf bound_ctrl:1
	v_pk_add_f32 v[146:147], v[146:147], v[98:99] neg_lo:[0,1] neg_hi:[0,1]
	s_nop 0
	v_add_f32_dpp v144, v144, v144 row_half_mirror row_mask:0xf bank_mask:0xf bound_ctrl:1
	v_pk_fma_f32 v[98:99], v[34:35], v[146:147], v[98:99]
	s_nop 0
	v_add_f32_dpp v144, v144, v144 row_mirror row_mask:0xf bank_mask:0xf bound_ctrl:1
	ds_bpermute_b32 v145, v102, v144
	s_and_saveexec_b64 s[4:5], s[0:1]
	s_cbranch_execz .LBB0_980
	s_waitcnt lgkmcnt(0)
	v_add_f32_e32 v144, v144, v145
	v_pk_mul_f32 v[144:145], v[98:99], v[144:145] op_sel_hi:[1,0]
	v_cvt_pk_bf16_f32 v146, v144, v145
	v_lshl_add_u64 v[144:145], v[80:81], 0, s[16:17]
	global_store_dword v[144:145], v146, off
